# attention loops: softmax row-sum chains as v_pk_add_f32 on register pairs (16+1 instead of 32 adds per step)
# baseline (speedup 1.0000x reference)
.LBB0_417:
	s_waitcnt lgkmcnt(7)
	v_mfma_f32_32x32x16_bf16 v[130:145], v[206:209], v[174:177], v[66:81]
	v_pk_add_f32 v[114:115], v[100:101], v[98:99]
	s_lshl_b32 s10, s10, 1
	v_pk_add_f32 v[114:115], v[102:103], v[114:115]
	v_add_u32_e32 v239, s10, v243
	v_cvt_pk_bf16_f32 v158, v98, v99
	v_cvt_pk_bf16_f32 v159, v100, v101
	s_nop 0
	v_pk_add_f32 v[98:99], v[104:105], v[114:115]
	s_waitcnt lgkmcnt(6)
	v_mfma_f32_32x32x16_bf16 v[114:129], v[202:205], v[174:177], v[66:81]
	v_pk_add_f32 v[98:99], v[106:107], v[98:99]
	v_cvt_pk_bf16_f32 v160, v102, v103
	v_cvt_pk_bf16_f32 v161, v104, v105
	s_waitcnt lgkmcnt(5)
	v_mfma_f32_32x32x16_bf16 v[130:145], v[198:201], v[170:173], v[130:145]
	v_pk_add_f32 v[98:99], v[108:109], v[98:99]
	v_pk_add_f32 v[98:99], v[110:111], v[98:99]
	v_cvt_pk_bf16_f32 v154, v106, v107
	v_cvt_pk_bf16_f32 v155, v108, v109
	s_waitcnt lgkmcnt(4)
	v_mfma_f32_32x32x16_bf16 v[114:129], v[194:197], v[170:173], v[114:129]
	v_pk_add_f32 v[98:99], v[112:113], v[98:99]
	v_pk_add_f32 v[102:103], v[82:83], v[98:99]
	v_cvt_pk_bf16_f32 v156, v110, v111
	v_cvt_pk_bf16_f32 v157, v112, v113
	ds_read_b64_tr_b16 v[98:99], v239 offset:24576
	ds_read_b64_tr_b16 v[100:101], v239 offset:25088
	s_waitcnt lgkmcnt(5)
	v_mfma_f32_32x32x16_bf16 v[130:145], v[190:193], v[166:169], v[130:145]
	v_pk_add_f32 v[102:103], v[84:85], v[102:103]
	v_pk_add_f32 v[102:103], v[86:87], v[102:103]
	v_cvt_pk_bf16_f32 v150, v82, v83
	v_cvt_pk_bf16_f32 v151, v84, v85
	ds_read_b64_tr_b16 v[82:83], v239 offset:28672
	ds_read_b64_tr_b16 v[84:85], v239 offset:29184
	s_waitcnt lgkmcnt(6)
	v_mfma_f32_32x32x16_bf16 v[114:129], v[186:189], v[166:169], v[114:129]
	v_pk_add_f32 v[102:103], v[88:89], v[102:103]
	v_pk_add_f32 v[102:103], v[90:91], v[102:103]
	v_cvt_pk_bf16_f32 v152, v86, v87
	v_cvt_pk_bf16_f32 v153, v88, v89
	ds_read_b64_tr_b16 v[86:87], v239 offset:25600
	ds_read_b64_tr_b16 v[88:89], v239 offset:26112
	s_waitcnt lgkmcnt(7)
	v_mfma_f32_32x32x16_bf16 v[130:145], v[182:185], v[162:165], v[130:145]
	v_pk_add_f32 v[102:103], v[92:93], v[102:103]
	v_pk_add_f32 v[102:103], v[94:95], v[102:103]
	v_cvt_pk_bf16_f32 v146, v90, v91
	v_cvt_pk_bf16_f32 v147, v92, v93
	ds_read_b64_tr_b16 v[90:91], v239 offset:29696
	ds_read_b64_tr_b16 v[92:93], v239 offset:30208
	s_waitcnt lgkmcnt(8)
	v_mfma_f32_32x32x16_bf16 v[114:129], v[178:181], v[162:165], v[114:129]
	v_pk_add_f32 v[102:103], v[96:97], v[102:103]
	v_add_f32_e32 v102, v102, v103
	v_cvt_pk_bf16_f32 v148, v94, v95
	v_cvt_pk_bf16_f32 v149, v96, v97
	v_lshl_add_u64 v[208:209], v[234:235], 0, s[20:21]
	v_lshl_add_u64 v[94:95], v[208:209], 0, s[46:47]
	s_add_i32 s10, s68, s41
	v_lshl_add_u64 v[206:207], v[236:237], 0, s[20:21]
	s_mov_b32 s11, m0
	s_mov_b32 m0, s10
	s_nop 0
	global_load_lds_dwordx4 v[94:95], off
	s_mov_b32 m0, s11
	v_lshl_add_u64 v[94:95], v[206:207], 0, s[48:49]
	s_lshl_b32 s10, s5, 1
	s_add_i32 s10, s10, s57
	s_mov_b32 s11, m0
	s_mov_b32 m0, s10
	s_nop 0
	global_load_lds_dwordx4 v[94:95], off
	s_mov_b32 m0, s11
	v_lshl_add_u64 v[94:95], v[206:207], 0, s[50:51]
	s_addk_i32 s10, 0x2000
	s_mov_b32 s11, m0
	s_mov_b32 m0, s10
	s_nop 0
	global_load_lds_dwordx4 v[94:95], off
	s_mov_b32 m0, s11
	v_max_f32_e32 v94, v130, v131
	v_max3_f32 v95, v132, v133, v115
	v_max3_f32 v94, v94, v114, v116
	v_max3_f32 v94, v94, v117, v134
	v_max3_f32 v95, v95, v136, v137
	v_max3_f32 v94, v94, v135, v118
	v_max3_f32 v95, v95, v120, v121
	v_max3_f32 v94, v94, v119, v138
	v_max3_f32 v95, v95, v140, v141
	v_max3_f32 v94, v94, v139, v122
	v_max3_f32 v95, v95, v124, v125
	v_max3_f32 v94, v94, v123, v142
	v_max3_f32 v95, v95, v144, v145
	v_max3_f32 v94, v94, v143, v126
	v_max3_f32 v95, v95, v128, v129
	v_max3_f32 v94, v94, v127, v95
	v_mov_b32_e32 v95, v94
	s_nop 1
	v_permlane32_swap_b32_e32 v94, v95
	v_max_f32_e32 v94, v94, v95
	v_cmp_lt_f32_e32 vcc, s84, v94
	s_cmp_lg_u64 vcc, 0
	v_add_f32_e32 v238, v238, v102
	s_cselect_b64 s[58:59], -1, 0
	s_cbranch_vccnz .LBB0_425

.LBB0_420:
	s_add_i32 s10, s5, 0x2000
	s_cmpk_lg_i32 s5, 0x4000
	s_cselect_b32 s88, s10, 0
	v_mfma_f32_32x32x16_bf16 v[98:113], v[82:85], v[174:177], v[66:81]
	v_pk_add_f32 v[86:87], v[132:133], v[130:131]
	s_lshl_b32 s10, s68, 1
	v_pk_add_f32 v[82:83], v[134:135], v[86:87]
	v_add_u32_e32 v239, s10, v243
	v_cvt_pk_bf16_f32 v158, v130, v131
	v_cvt_pk_bf16_f32 v159, v132, v133
	s_nop 0
	v_pk_add_f32 v[82:83], v[136:137], v[82:83]
	v_pk_add_f32 v[130:131], v[138:139], v[82:83]
	v_mfma_f32_32x32x16_bf16 v[82:97], v[198:201], v[174:177], v[66:81]
	v_cvt_pk_bf16_f32 v160, v134, v135
	v_cvt_pk_bf16_f32 v161, v136, v137
	v_mfma_f32_32x32x16_bf16 v[98:113], v[202:205], v[170:173], v[98:113]
	v_pk_add_f32 v[130:131], v[140:141], v[130:131]
	v_pk_add_f32 v[130:131], v[142:143], v[130:131]
	v_cvt_pk_bf16_f32 v154, v138, v139
	v_cvt_pk_bf16_f32 v155, v140, v141
	v_mfma_f32_32x32x16_bf16 v[82:97], v[194:197], v[170:173], v[82:97]
	v_pk_add_f32 v[130:131], v[144:145], v[130:131]
	v_pk_add_f32 v[134:135], v[114:115], v[130:131]
	v_cvt_pk_bf16_f32 v156, v142, v143
	v_cvt_pk_bf16_f32 v157, v144, v145
	ds_read_b64_tr_b16 v[130:131], v239 offset:24576
	ds_read_b64_tr_b16 v[132:133], v239 offset:25088
	v_mfma_f32_32x32x16_bf16 v[98:113], v[190:193], v[166:169], v[98:113]
	v_pk_add_f32 v[134:135], v[116:117], v[134:135]
	v_pk_add_f32 v[134:135], v[118:119], v[134:135]
	v_cvt_pk_bf16_f32 v150, v114, v115
	v_cvt_pk_bf16_f32 v151, v116, v117
	ds_read_b64_tr_b16 v[114:115], v239 offset:28672
	ds_read_b64_tr_b16 v[116:117], v239 offset:29184
	v_mfma_f32_32x32x16_bf16 v[82:97], v[186:189], v[166:169], v[82:97]
	v_pk_add_f32 v[134:135], v[120:121], v[134:135]
	v_pk_add_f32 v[134:135], v[122:123], v[134:135]
	v_cvt_pk_bf16_f32 v152, v118, v119
	v_cvt_pk_bf16_f32 v153, v120, v121
	ds_read_b64_tr_b16 v[118:119], v239 offset:25600
	ds_read_b64_tr_b16 v[120:121], v239 offset:26112
	v_mfma_f32_32x32x16_bf16 v[98:113], v[182:185], v[162:165], v[98:113]
	v_pk_add_f32 v[134:135], v[124:125], v[134:135]
	v_pk_add_f32 v[134:135], v[126:127], v[134:135]
	v_cvt_pk_bf16_f32 v146, v122, v123
	v_cvt_pk_bf16_f32 v147, v124, v125
	ds_read_b64_tr_b16 v[122:123], v239 offset:29696
	ds_read_b64_tr_b16 v[124:125], v239 offset:30208
	v_mfma_f32_32x32x16_bf16 v[82:97], v[178:181], v[162:165], v[82:97]
	v_pk_add_f32 v[134:135], v[128:129], v[134:135]
	v_add_f32_e32 v134, v134, v135
	v_cvt_pk_bf16_f32 v148, v126, v127
	v_cvt_pk_bf16_f32 v149, v128, v129
	v_lshl_add_u64 v[126:127], v[208:209], 0, s[52:53]
	s_add_i32 s10, s5, s41
	s_mov_b32 s11, m0
	s_mov_b32 m0, s10
	s_nop 0
	global_load_lds_dwordx4 v[126:127], off
	s_mov_b32 m0, s11
	s_mov_b64 s[10:11], 0x7078200
	v_lshl_add_u64 v[126:127], v[206:207], 0, s[10:11]
	s_lshl_b32 s10, s88, 1
	s_add_i32 s58, s10, s57
	s_mov_b32 s10, m0
	s_mov_b32 m0, s58
	s_nop 0
	global_load_lds_dwordx4 v[126:127], off
	s_mov_b32 m0, s10
	s_mov_b64 s[10:11], 0x7078280
	v_lshl_add_u64 v[126:127], v[206:207], 0, s[10:11]
	s_add_i32 s10, s58, 0x2000
	s_mov_b32 s11, m0
	s_mov_b32 m0, s10
	s_nop 0
	global_load_lds_dwordx4 v[126:127], off
	s_mov_b32 m0, s11
	v_max_f32_e32 v126, v98, v99
	v_max3_f32 v127, v100, v101, v83
	v_max3_f32 v126, v126, v82, v84
	v_max3_f32 v126, v126, v85, v102
	v_max3_f32 v127, v127, v104, v105
	v_max3_f32 v126, v126, v103, v86
	v_max3_f32 v127, v127, v88, v89
	v_max3_f32 v126, v126, v87, v106
	v_max3_f32 v127, v127, v108, v109
	v_max3_f32 v126, v126, v107, v90
	v_max3_f32 v127, v127, v92, v93
	v_max3_f32 v126, v126, v91, v110
	v_max3_f32 v127, v127, v112, v113
	v_max3_f32 v126, v126, v111, v94
	v_max3_f32 v127, v127, v96, v97
	v_max3_f32 v126, v126, v95, v127
	v_mov_b32_e32 v127, v126
	s_nop 1
	v_permlane32_swap_b32_e32 v126, v127
	v_max_f32_e32 v126, v126, v127
	v_cmp_lt_f32_e32 vcc, s84, v126
	s_cmp_lg_u64 vcc, 0
	v_add_f32_e32 v238, v238, v134
	s_cselect_b64 s[58:59], -1, 0
	s_cbranch_vccnz .LBB0_428

.LBB0_491:
	v_add_u32_e32 v190, s4, v243
	ds_read_b64_tr_b16 v[178:179], v190 offset:24576
	ds_read_b64_tr_b16 v[180:181], v190 offset:25088
	s_waitcnt lgkmcnt(9)
	v_mfma_f32_32x32x16_bf16 v[98:113], v[174:177], v[142:145], v[34:49]
	v_pk_add_f32 v[82:83], v[68:69], v[66:67]
	v_pk_add_f32 v[82:83], v[70:71], v[82:83]
	v_cvt_pk_bf16_f32 v138, v66, v67
	v_cvt_pk_bf16_f32 v139, v68, v69
	ds_read_b64_tr_b16 v[174:175], v190 offset:28672
	ds_read_b64_tr_b16 v[176:177], v190 offset:29184
	v_pk_add_f32 v[66:67], v[72:73], v[82:83]
	s_waitcnt lgkmcnt(10)
	v_mfma_f32_32x32x16_bf16 v[82:97], v[170:173], v[142:145], v[34:49]
	v_pk_add_f32 v[118:119], v[74:75], v[66:67]
	v_cvt_pk_bf16_f32 v140, v70, v71
	v_cvt_pk_bf16_f32 v141, v72, v73
	ds_read_b64_tr_b16 v[66:67], v190 offset:25600
	ds_read_b64_tr_b16 v[68:69], v190 offset:26112
	s_waitcnt lgkmcnt(11)
	v_mfma_f32_32x32x16_bf16 v[98:113], v[166:169], v[130:133], v[98:113]
	v_pk_add_f32 v[70:71], v[76:77], v[118:119]
	v_pk_add_f32 v[118:119], v[78:79], v[70:71]
	v_cvt_pk_bf16_f32 v134, v74, v75
	v_cvt_pk_bf16_f32 v135, v76, v77
	ds_read_b64_tr_b16 v[70:71], v190 offset:29696
	ds_read_b64_tr_b16 v[72:73], v190 offset:30208
	s_waitcnt lgkmcnt(12)
	v_mfma_f32_32x32x16_bf16 v[82:97], v[162:165], v[130:133], v[82:97]
	v_pk_add_f32 v[74:75], v[80:81], v[118:119]
	v_pk_add_f32 v[118:119], v[50:51], v[74:75]
	v_cvt_pk_bf16_f32 v136, v78, v79
	v_cvt_pk_bf16_f32 v137, v80, v81
	ds_read_b64_tr_b16 v[74:75], v190 offset:26624
	ds_read_b64_tr_b16 v[76:77], v190 offset:27136
	s_waitcnt lgkmcnt(13)
	v_mfma_f32_32x32x16_bf16 v[98:113], v[158:161], v[122:125], v[98:113]
	v_pk_add_f32 v[78:79], v[52:53], v[118:119]
	v_pk_add_f32 v[78:79], v[54:55], v[78:79]
	v_cvt_pk_bf16_f32 v126, v50, v51
	v_cvt_pk_bf16_f32 v127, v52, v53
	ds_read_b64_tr_b16 v[50:51], v190 offset:30720
	ds_read_b64_tr_b16 v[52:53], v190 offset:31232
	s_waitcnt lgkmcnt(14)
	v_mfma_f32_32x32x16_bf16 v[82:97], v[154:157], v[122:125], v[82:97]
	v_pk_add_f32 v[78:79], v[56:57], v[78:79]
	v_pk_add_f32 v[78:79], v[58:59], v[78:79]
	v_cvt_pk_bf16_f32 v128, v54, v55
	v_cvt_pk_bf16_f32 v129, v56, v57
	ds_read_b64_tr_b16 v[54:55], v190 offset:27648
	ds_read_b64_tr_b16 v[56:57], v190 offset:28160
	s_waitcnt lgkmcnt(14)
	v_mfma_f32_32x32x16_bf16 v[98:113], v[150:153], v[114:117], v[98:113]
	v_pk_add_f32 v[78:79], v[60:61], v[78:79]
	v_pk_add_f32 v[78:79], v[62:63], v[78:79]
	v_cvt_pk_bf16_f32 v118, v58, v59
	v_cvt_pk_bf16_f32 v119, v60, v61
	ds_read_b64_tr_b16 v[58:59], v190 offset:31744
	ds_read_b64_tr_b16 v[60:61], v190 offset:32256
	v_mfma_f32_32x32x16_bf16 v[82:97], v[146:149], v[114:117], v[82:97]
	v_pk_add_f32 v[78:79], v[64:65], v[78:79]
	v_add_f32_e32 v78, v78, v79
	v_cvt_pk_bf16_f32 v120, v62, v63
	v_cvt_pk_bf16_f32 v121, v64, v65
	v_lshl_add_u64 v[62:63], v[188:189], 0, s[54:55]
	s_add_i32 s4, s40, s37
	s_mov_b32 s5, m0
	s_mov_b32 m0, s4
	s_nop 0
	global_load_lds_dwordx4 v[62:63], off
	s_mov_b32 m0, s5
	v_lshl_add_u64 v[62:63], v[186:187], 0, s[54:55]
	s_add_i32 s4, s20, s38
	s_mov_b32 s5, m0
	s_mov_b32 m0, s4
	s_nop 0
	global_load_lds_dwordx4 v[62:63], off
	s_mov_b32 m0, s5
	v_max_f32_e32 v62, v98, v99
	v_max3_f32 v63, v100, v101, v83
	v_max3_f32 v62, v62, v82, v84
	v_max3_f32 v62, v62, v85, v102
	v_max3_f32 v63, v63, v104, v105
	v_max3_f32 v62, v62, v103, v86
	v_max3_f32 v63, v63, v88, v89
	v_max3_f32 v62, v62, v87, v106
	v_max3_f32 v63, v63, v108, v109
	v_max3_f32 v62, v62, v107, v90
	v_max3_f32 v63, v63, v92, v93
	v_max3_f32 v62, v62, v91, v110
	v_max3_f32 v63, v63, v112, v113
	v_max3_f32 v62, v62, v111, v94
	v_max3_f32 v63, v63, v96, v97
	v_max3_f32 v62, v62, v95, v63
	v_mov_b32_e32 v63, v62
	s_nop 1
	v_permlane32_swap_b32_e32 v62, v63
	v_max_f32_e32 v62, v62, v63
	v_cmp_lt_f32_e32 vcc, s84, v62
	s_cmp_lg_u64 vcc, 0
	v_add_f32_e32 v190, v195, v78
	s_cselect_b64 s[4:5], -1, 0
	s_cbranch_vccnz .LBB0_499

.LBB0_494:
	s_add_i32 s4, s20, 0x2000
	s_cmpk_lg_i32 s20, 0x4000
	s_cselect_b32 s39, s4, 0
	v_add_u32_e32 v191, s40, v243
	ds_read_b64_tr_b16 v[150:151], v191 offset:24576
	ds_read_b64_tr_b16 v[152:153], v191 offset:25088
	s_waitcnt lgkmcnt(9)
	v_mfma_f32_32x32x16_bf16 v[66:81], v[62:65], v[142:145], v[34:49]
	v_pk_add_f32 v[50:51], v[100:101], v[98:99]
	v_pk_add_f32 v[50:51], v[102:103], v[50:51]
	v_cvt_pk_bf16_f32 v138, v98, v99
	v_cvt_pk_bf16_f32 v139, v100, v101
	ds_read_b64_tr_b16 v[146:147], v191 offset:28672
	ds_read_b64_tr_b16 v[148:149], v191 offset:29184
	v_pk_add_f32 v[50:51], v[104:105], v[50:51]
	v_pk_add_f32 v[118:119], v[106:107], v[50:51]
	s_waitcnt lgkmcnt(10)
	v_mfma_f32_32x32x16_bf16 v[50:65], v[174:177], v[142:145], v[34:49]
	v_cvt_pk_bf16_f32 v140, v102, v103
	v_cvt_pk_bf16_f32 v141, v104, v105
	ds_read_b64_tr_b16 v[98:99], v191 offset:25600
	ds_read_b64_tr_b16 v[100:101], v191 offset:26112
	s_waitcnt lgkmcnt(11)
	v_mfma_f32_32x32x16_bf16 v[66:81], v[178:181], v[130:133], v[66:81]
	v_pk_add_f32 v[102:103], v[108:109], v[118:119]
	v_pk_add_f32 v[118:119], v[110:111], v[102:103]
	v_cvt_pk_bf16_f32 v134, v106, v107
	v_cvt_pk_bf16_f32 v135, v108, v109
	ds_read_b64_tr_b16 v[102:103], v191 offset:29696
	ds_read_b64_tr_b16 v[104:105], v191 offset:30208
	s_waitcnt lgkmcnt(12)
	v_mfma_f32_32x32x16_bf16 v[50:65], v[170:173], v[130:133], v[50:65]
	v_pk_add_f32 v[106:107], v[112:113], v[118:119]
	v_pk_add_f32 v[118:119], v[82:83], v[106:107]
	v_cvt_pk_bf16_f32 v136, v110, v111
	v_cvt_pk_bf16_f32 v137, v112, v113
	ds_read_b64_tr_b16 v[106:107], v191 offset:26624
	ds_read_b64_tr_b16 v[108:109], v191 offset:27136
	s_waitcnt lgkmcnt(13)
	v_mfma_f32_32x32x16_bf16 v[66:81], v[166:169], v[122:125], v[66:81]
	v_pk_add_f32 v[110:111], v[84:85], v[118:119]
	v_pk_add_f32 v[110:111], v[86:87], v[110:111]
	v_cvt_pk_bf16_f32 v126, v82, v83
	v_cvt_pk_bf16_f32 v127, v84, v85
	ds_read_b64_tr_b16 v[82:83], v191 offset:30720
	ds_read_b64_tr_b16 v[84:85], v191 offset:31232
	s_waitcnt lgkmcnt(14)
	v_mfma_f32_32x32x16_bf16 v[50:65], v[162:165], v[122:125], v[50:65]
	v_pk_add_f32 v[110:111], v[88:89], v[110:111]
	v_pk_add_f32 v[110:111], v[90:91], v[110:111]
	v_cvt_pk_bf16_f32 v128, v86, v87
	v_cvt_pk_bf16_f32 v129, v88, v89
	ds_read_b64_tr_b16 v[86:87], v191 offset:27648
	ds_read_b64_tr_b16 v[88:89], v191 offset:28160
	s_waitcnt lgkmcnt(14)
	v_mfma_f32_32x32x16_bf16 v[66:81], v[158:161], v[114:117], v[66:81]
	v_pk_add_f32 v[110:111], v[92:93], v[110:111]
	v_pk_add_f32 v[110:111], v[94:95], v[110:111]
	v_cvt_pk_bf16_f32 v118, v90, v91
	v_cvt_pk_bf16_f32 v119, v92, v93
	ds_read_b64_tr_b16 v[90:91], v191 offset:31744
	ds_read_b64_tr_b16 v[92:93], v191 offset:32256
	v_mfma_f32_32x32x16_bf16 v[50:65], v[154:157], v[114:117], v[50:65]
	v_pk_add_f32 v[110:111], v[96:97], v[110:111]
	v_add_f32_e32 v110, v110, v111
	v_cvt_pk_bf16_f32 v120, v94, v95
	v_cvt_pk_bf16_f32 v121, v96, v97
	v_max_f32_e32 v94, v66, v67
	s_nop 3
	v_max3_f32 v95, v68, v69, v51
	v_max3_f32 v94, v94, v50, v52
	v_max3_f32 v94, v94, v53, v70
	v_max3_f32 v95, v95, v72, v73
	v_max3_f32 v94, v94, v71, v54
	v_max3_f32 v95, v95, v56, v57
	v_max3_f32 v94, v94, v55, v74
	v_max3_f32 v95, v95, v76, v77
	v_max3_f32 v94, v94, v75, v58
	v_max3_f32 v95, v95, v60, v61
	v_max3_f32 v94, v94, v59, v78
	v_max3_f32 v95, v95, v80, v81
	v_max3_f32 v94, v94, v79, v62
	v_max3_f32 v95, v95, v64, v65
	v_max3_f32 v94, v94, v63, v95
	v_mov_b32_e32 v95, v94
	s_nop 1
	v_permlane32_swap_b32_e32 v94, v95
	s_add_i32 s4, s20, s37
	s_mov_b32 s5, m0
	s_mov_b32 m0, s4
	s_nop 0
	global_load_lds_dwordx4 v[188:189], off
	s_mov_b32 m0, s5
	v_max_f32_e32 v94, v94, v95
	s_add_i32 s4, s39, s38
	s_mov_b32 s5, m0
	s_mov_b32 m0, s4
	s_nop 0
	global_load_lds_dwordx4 v[186:187], off
	s_mov_b32 m0, s5
	v_cmp_lt_f32_e32 vcc, s84, v94
	s_cmp_lg_u64 vcc, 0
	v_add_f32_e32 v195, v190, v110
	s_cselect_b64 s[4:5], -1, 0
	s_cbranch_vccnz .LBB0_502
